# v77 + hand-written SwiGLU epilogue in ph_gu: packed f32 math on natural accumulator pairs (same per-element op order), batched row-scale reductions, saddr stores
# speedup vs baseline: 1.0067x; 1.0007x over previous
; DI unsigned pk2(float lo, float hi) { unsigned r; asm("v_cvt_pk_bf16_f32 %0, %1, %2" : "=v"(r) : "v"(lo), "v"(hi)); return r; }
; DI float fsilu(float x) { return x * fsigmoid(x); }
;     DI void operator()(const f32x4 (&acc)[2][2][4][2], const Unit& u, int wr, int wc, int fr, int fq) const {
;         const int col0 = u.pn * 128 + wc * 32 + 8 * fq;
;         const int rowb = u.pm * BM + wr * 64 + fr;
;         f32x4 sl[2][4];
; #pragma unroll
;         for (int ai = 0; ai < 2; ++ai)
; #pragma unroll
;             for (int m = 0; m < 4; ++m) sl[ai][m] = *(const f32x4*)(slots + (size_t)(rowb + ai * HALF + m * 16) * 16 + 4 * fq);
;         asm volatile("" ::: "memory");
; #pragma unroll
;         for (int ai = 0; ai < 2; ++ai)
; #pragma unroll
;             for (int m = 0; m < 4; ++m) {
;                 const int row = rowb + ai * HALF + m * 16;
;                 float t = (sl[ai][m][0] + sl[ai][m][1]) + (sl[ai][m][2] + sl[ai][m][3]);
;                 t += __shfl_xor(t, 16); t += __shfl_xor(t, 32);
;                 const float rs = __builtin_amdgcn_rsqf(t * (1.0f / D) + EPS);
;                 float h[8];
; #pragma unroll
;                 for (int n = 0; n < 2; ++n)
; #pragma unroll
;                     for (int j = 0; j < 4; ++j) { const float gv = acc[ai][0][m][n][j] * rs, uv = acc[ai][1][m][n][j] * rs; h[n * 4 + j] = fsilu(gv) * uv; }
;                 u32x4 w; w.x = pk2(h[0], h[1]); w.y = pk2(h[2], h[3]); w.z = pk2(h[4], h[5]); w.w = pk2(h[6], h[7]);
;                 *(u32x4*)(H + (size_t)row * FF + col0) = w;
.LBB0_704:
	v_lshl_add_u32 v178, s54, 8, v1
	v_lshlrev_b32_e32 v102, 6, v178
	v_mov_b32_e32 v103, 0
	v_add_u32_e32 v104, 0x2000, v102
	v_mov_b32_e32 v105, 0
	v_lshl_add_u64 v[102:103], v[160:161], 0, v[102:103]
	v_lshl_add_u64 v[104:105], v[160:161], 0, v[104:105]
	global_load_dwordx4 v[206:209], v[102:103], off
	global_load_dwordx4 v[210:213], v[102:103], off offset:1024
	global_load_dwordx4 v[214:217], v[102:103], off offset:2048
	global_load_dwordx4 v[218:221], v[102:103], off offset:3072
	global_load_dwordx4 v[222:225], v[104:105], off
	global_load_dwordx4 v[200:203], v[104:105], off offset:1024
	global_load_dwordx4 v[188:191], v[104:105], off offset:2048
	global_load_dwordx4 v[140:143], v[104:105], off offset:3072
	v_xor_b32_e32 v204, 16, v249
	v_xor_b32_e32 v205, 32, v249
	v_lshlrev_b32_e32 v204, 2, v204
	v_lshlrev_b32_e32 v205, 2, v205
	v_lshl_or_b32 v179, s17, 7, v185
	v_mul_lo_u32 v166, v178, s92
	v_lshlrev_b32_e32 v179, 1, v179
	s_mov_b32 s98, 0xbfb8aa3b
	s_mov_b32 s100, 1.0
	v_add_u32_e32 v166, v166, v179
	v_add_u32_e32 v167, 0x16000, v166
	v_add_u32_e32 v168, 0x2c000, v166
	v_add_u32_e32 v169, 0x42000, v166
	v_add_u32_e32 v170, 0xb0000, v166
	v_add_u32_e32 v171, 0xc6000, v166
	v_add_u32_e32 v172, 0xdc000, v166
	v_add_u32_e32 v173, 0xf2000, v166
	s_waitcnt vmcnt(7)
	v_add_f32_e32 v206, v206, v207
	v_add_f32_e32 v208, v208, v209
	v_add_f32_e32 v206, v206, v208
	ds_bpermute_b32 v207, v204, v206
	s_waitcnt vmcnt(6)
	v_add_f32_e32 v210, v210, v211
	v_add_f32_e32 v212, v212, v213
	v_add_f32_e32 v210, v210, v212
	ds_bpermute_b32 v211, v204, v210
	s_waitcnt vmcnt(5)
	v_add_f32_e32 v214, v214, v215
	v_add_f32_e32 v216, v216, v217
	v_add_f32_e32 v214, v214, v216
	ds_bpermute_b32 v215, v204, v214
	s_waitcnt vmcnt(4)
	v_add_f32_e32 v218, v218, v219
	v_add_f32_e32 v220, v220, v221
	v_add_f32_e32 v218, v218, v220
	ds_bpermute_b32 v219, v204, v218
	s_waitcnt vmcnt(3)
	v_add_f32_e32 v222, v222, v223
	v_add_f32_e32 v224, v224, v225
	v_add_f32_e32 v222, v222, v224
	ds_bpermute_b32 v223, v204, v222
	s_waitcnt vmcnt(2)
	v_add_f32_e32 v200, v200, v201
	v_add_f32_e32 v202, v202, v203
	v_add_f32_e32 v200, v200, v202
	ds_bpermute_b32 v201, v204, v200
	s_waitcnt vmcnt(1)
	v_add_f32_e32 v188, v188, v189
	v_add_f32_e32 v190, v190, v191
	v_add_f32_e32 v188, v188, v190
	ds_bpermute_b32 v189, v204, v188
	s_waitcnt vmcnt(0)
	v_add_f32_e32 v140, v140, v141
	v_add_f32_e32 v142, v142, v143
	v_add_f32_e32 v140, v140, v142
	ds_bpermute_b32 v141, v204, v140
	s_waitcnt lgkmcnt(0)
	v_add_f32_e32 v206, v206, v207
	ds_bpermute_b32 v207, v205, v206
	v_add_f32_e32 v210, v210, v211
	ds_bpermute_b32 v211, v205, v210
	v_add_f32_e32 v214, v214, v215
	ds_bpermute_b32 v215, v205, v214
	v_add_f32_e32 v218, v218, v219
	ds_bpermute_b32 v219, v205, v218
	v_add_f32_e32 v222, v222, v223
	ds_bpermute_b32 v223, v205, v222
	v_add_f32_e32 v200, v200, v201
	ds_bpermute_b32 v201, v205, v200
	v_add_f32_e32 v188, v188, v189
	ds_bpermute_b32 v189, v205, v188
	v_add_f32_e32 v140, v140, v141
	ds_bpermute_b32 v141, v205, v140
	s_waitcnt lgkmcnt(0)
	v_add_f32_e32 v206, v206, v207
	v_add_f32_e32 v210, v210, v211
	v_add_f32_e32 v214, v214, v215
	v_add_f32_e32 v218, v218, v219
	v_add_f32_e32 v222, v222, v223
	v_add_f32_e32 v200, v200, v201
	v_add_f32_e32 v188, v188, v189
	v_add_f32_e32 v140, v140, v141
	v_fmamk_f32 v206, v206, 0x3a800000, v243
	v_fmamk_f32 v210, v210, 0x3a800000, v243
	v_fmamk_f32 v214, v214, 0x3a800000, v243
	v_fmamk_f32 v218, v218, 0x3a800000, v243
	v_fmamk_f32 v222, v222, 0x3a800000, v243
	v_fmamk_f32 v200, v200, 0x3a800000, v243
	v_fmamk_f32 v188, v188, 0x3a800000, v243
	v_fmamk_f32 v140, v140, 0x3a800000, v243
	v_rsq_f32_e32 v174, v206
	v_rsq_f32_e32 v176, v210
	v_rsq_f32_e32 v180, v214
	v_rsq_f32_e32 v182, v218
	v_rsq_f32_e32 v144, v222
	v_rsq_f32_e32 v146, v200
	v_rsq_f32_e32 v148, v188
	v_rsq_f32_e32 v150, v140
	v_pk_mul_f32 v[136:137], v[136:137], v[174:175] op_sel_hi:[1,0]
	v_pk_mul_f32 v[138:139], v[138:139], v[174:175] op_sel_hi:[1,0]
	v_pk_mul_f32 v[128:129], v[128:129], v[174:175] op_sel_hi:[1,0]
	v_pk_mul_f32 v[130:131], v[130:131], v[174:175] op_sel_hi:[1,0]
	v_pk_mul_f32 v[206:207], v[136:137], s[98:99] op_sel_hi:[1,0]
	v_pk_mul_f32 v[208:209], v[138:139], s[98:99] op_sel_hi:[1,0]
	v_pk_mul_f32 v[210:211], v[128:129], s[98:99] op_sel_hi:[1,0]
	v_pk_mul_f32 v[212:213], v[130:131], s[98:99] op_sel_hi:[1,0]
	v_pk_mul_f32 v[82:83], v[82:83], v[174:175] op_sel_hi:[1,0]
	v_pk_mul_f32 v[84:85], v[84:85], v[174:175] op_sel_hi:[1,0]
	v_pk_mul_f32 v[124:125], v[124:125], v[174:175] op_sel_hi:[1,0]
	v_pk_mul_f32 v[126:127], v[126:127], v[174:175] op_sel_hi:[1,0]
	v_exp_f32_e32 v206, v206
	v_exp_f32_e32 v207, v207
	v_exp_f32_e32 v208, v208
	v_exp_f32_e32 v209, v209
	v_exp_f32_e32 v210, v210
	v_exp_f32_e32 v211, v211
	v_exp_f32_e32 v212, v212
	v_exp_f32_e32 v213, v213
	v_pk_add_f32 v[206:207], v[206:207], s[100:101] op_sel_hi:[1,0]
	v_pk_add_f32 v[208:209], v[208:209], s[100:101] op_sel_hi:[1,0]
	v_pk_add_f32 v[210:211], v[210:211], s[100:101] op_sel_hi:[1,0]
	v_pk_add_f32 v[212:213], v[212:213], s[100:101] op_sel_hi:[1,0]
	v_rcp_f32_e32 v206, v206
	v_rcp_f32_e32 v207, v207
	v_rcp_f32_e32 v208, v208
	v_rcp_f32_e32 v209, v209
	v_rcp_f32_e32 v210, v210
	v_rcp_f32_e32 v211, v211
	v_rcp_f32_e32 v212, v212
	v_rcp_f32_e32 v213, v213
	v_pk_mul_f32 v[206:207], v[136:137], v[206:207]
	v_pk_mul_f32 v[208:209], v[138:139], v[208:209]
	v_pk_mul_f32 v[210:211], v[128:129], v[210:211]
	v_pk_mul_f32 v[212:213], v[130:131], v[212:213]
	v_pk_mul_f32 v[206:207], v[82:83], v[206:207]
	v_pk_mul_f32 v[208:209], v[84:85], v[208:209]
	v_pk_mul_f32 v[210:211], v[124:125], v[210:211]
; DI unsigned pk2(float lo, float hi) { unsigned r; asm("v_cvt_pk_bf16_f32 %0, %1, %2" : "=v"(r) : "v"(lo), "v"(hi)); return r; }
; DI float fsilu(float x) { return x * fsigmoid(x); }
;     DI void operator()(const f32x4 (&acc)[2][2][4][2], const Unit& u, int wr, int wc, int fr, int fq) const {
;     ...
;             for (int m = 0; m < 4; ++m) {
;                 const int row = rowb + ai * HALF + m * 16;
;                 float t = (sl[ai][m][0] + sl[ai][m][1]) + (sl[ai][m][2] + sl[ai][m][3]);
;                 t += __shfl_xor(t, 16); t += __shfl_xor(t, 32);
;                 const float rs = __builtin_amdgcn_rsqf(t * (1.0f / D) + EPS);
;                 float h[8];
; #pragma unroll
;                 for (int n = 0; n < 2; ++n)
; #pragma unroll
;                     for (int j = 0; j < 4; ++j) { const float gv = acc[ai][0][m][n][j] * rs, uv = acc[ai][1][m][n][j] * rs; h[n * 4 + j] = fsilu(gv) * uv; }
;                 u32x4 w; w.x = pk2(h[0], h[1]); w.y = pk2(h[2], h[3]); w.z = pk2(h[4], h[5]); w.w = pk2(h[6], h[7]);
;                 *(u32x4*)(H + (size_t)row * FF + col0) = w;
;             }
	v_pk_mul_f32 v[212:213], v[126:127], v[212:213]
	v_cvt_pk_bf16_f32 v214, v206, v207
	v_cvt_pk_bf16_f32 v215, v208, v209
	v_cvt_pk_bf16_f32 v216, v210, v211
	v_cvt_pk_bf16_f32 v217, v212, v213
	global_store_dwordx4 v166, v[214:217], s[8:9]
	v_pk_mul_f32 v[118:119], v[118:119], v[176:177] op_sel_hi:[1,0]
	v_pk_mul_f32 v[120:121], v[120:121], v[176:177] op_sel_hi:[1,0]
	v_pk_mul_f32 v[110:111], v[110:111], v[176:177] op_sel_hi:[1,0]
	v_pk_mul_f32 v[112:113], v[112:113], v[176:177] op_sel_hi:[1,0]
	v_pk_mul_f32 v[218:219], v[118:119], s[98:99] op_sel_hi:[1,0]
	v_pk_mul_f32 v[220:221], v[120:121], s[98:99] op_sel_hi:[1,0]
	v_pk_mul_f32 v[222:223], v[110:111], s[98:99] op_sel_hi:[1,0]
	v_pk_mul_f32 v[224:225], v[112:113], s[98:99] op_sel_hi:[1,0]
	v_pk_mul_f32 v[114:115], v[114:115], v[176:177] op_sel_hi:[1,0]
	v_pk_mul_f32 v[116:117], v[116:117], v[176:177] op_sel_hi:[1,0]
	v_pk_mul_f32 v[106:107], v[106:107], v[176:177] op_sel_hi:[1,0]
	v_pk_mul_f32 v[108:109], v[108:109], v[176:177] op_sel_hi:[1,0]
	v_exp_f32_e32 v218, v218
	v_exp_f32_e32 v219, v219
	v_exp_f32_e32 v220, v220
	v_exp_f32_e32 v221, v221
	v_exp_f32_e32 v222, v222
	v_exp_f32_e32 v223, v223
	v_exp_f32_e32 v224, v224
	v_exp_f32_e32 v225, v225
	v_pk_add_f32 v[218:219], v[218:219], s[100:101] op_sel_hi:[1,0]
	v_pk_add_f32 v[220:221], v[220:221], s[100:101] op_sel_hi:[1,0]
	v_pk_add_f32 v[222:223], v[222:223], s[100:101] op_sel_hi:[1,0]
	v_pk_add_f32 v[224:225], v[224:225], s[100:101] op_sel_hi:[1,0]
	v_rcp_f32_e32 v218, v218
	v_rcp_f32_e32 v219, v219
	v_rcp_f32_e32 v220, v220
	v_rcp_f32_e32 v221, v221
	v_rcp_f32_e32 v222, v222
	v_rcp_f32_e32 v223, v223
	v_rcp_f32_e32 v224, v224
	v_rcp_f32_e32 v225, v225
	v_pk_mul_f32 v[218:219], v[118:119], v[218:219]
	v_pk_mul_f32 v[220:221], v[120:121], v[220:221]
	v_pk_mul_f32 v[222:223], v[110:111], v[222:223]
	v_pk_mul_f32 v[224:225], v[112:113], v[224:225]
	v_pk_mul_f32 v[218:219], v[114:115], v[218:219]
	v_pk_mul_f32 v[220:221], v[116:117], v[220:221]
	v_pk_mul_f32 v[222:223], v[106:107], v[222:223]
	v_pk_mul_f32 v[224:225], v[108:109], v[224:225]
	v_cvt_pk_bf16_f32 v200, v218, v219
	v_cvt_pk_bf16_f32 v201, v220, v221
	v_cvt_pk_bf16_f32 v202, v222, v223
	v_cvt_pk_bf16_f32 v203, v224, v225
	global_store_dwordx4 v167, v[200:203], s[8:9]
	v_pk_mul_f32 v[98:99], v[98:99], v[180:181] op_sel_hi:[1,0]
	v_pk_mul_f32 v[100:101], v[100:101], v[180:181] op_sel_hi:[1,0]
	v_pk_mul_f32 v[90:91], v[90:91], v[180:181] op_sel_hi:[1,0]
	v_pk_mul_f32 v[92:93], v[92:93], v[180:181] op_sel_hi:[1,0]
	v_pk_mul_f32 v[206:207], v[98:99], s[98:99] op_sel_hi:[1,0]
	v_pk_mul_f32 v[208:209], v[100:101], s[98:99] op_sel_hi:[1,0]
	v_pk_mul_f32 v[210:211], v[90:91], s[98:99] op_sel_hi:[1,0]
	v_pk_mul_f32 v[212:213], v[92:93], s[98:99] op_sel_hi:[1,0]
	v_pk_mul_f32 v[94:95], v[94:95], v[180:181] op_sel_hi:[1,0]
	v_pk_mul_f32 v[96:97], v[96:97], v[180:181] op_sel_hi:[1,0]
	v_pk_mul_f32 v[86:87], v[86:87], v[180:181] op_sel_hi:[1,0]
	v_pk_mul_f32 v[88:89], v[88:89], v[180:181] op_sel_hi:[1,0]
	v_exp_f32_e32 v206, v206
	v_exp_f32_e32 v207, v207
	v_exp_f32_e32 v208, v208
	v_exp_f32_e32 v209, v209
	v_exp_f32_e32 v210, v210
	v_exp_f32_e32 v211, v211
	v_exp_f32_e32 v212, v212
	v_exp_f32_e32 v213, v213
	v_pk_add_f32 v[206:207], v[206:207], s[100:101] op_sel_hi:[1,0]
	v_pk_add_f32 v[208:209], v[208:209], s[100:101] op_sel_hi:[1,0]
	v_pk_add_f32 v[210:211], v[210:211], s[100:101] op_sel_hi:[1,0]
	v_pk_add_f32 v[212:213], v[212:213], s[100:101] op_sel_hi:[1,0]
	v_rcp_f32_e32 v206, v206
	v_rcp_f32_e32 v207, v207
	v_rcp_f32_e32 v208, v208
	v_rcp_f32_e32 v209, v209
	v_rcp_f32_e32 v210, v210
	v_rcp_f32_e32 v211, v211
	v_rcp_f32_e32 v212, v212
	v_rcp_f32_e32 v213, v213
	v_pk_mul_f32 v[206:207], v[98:99], v[206:207]
	v_pk_mul_f32 v[208:209], v[100:101], v[208:209]
	v_pk_mul_f32 v[210:211], v[90:91], v[210:211]
	v_pk_mul_f32 v[212:213], v[92:93], v[212:213]
	v_pk_mul_f32 v[206:207], v[94:95], v[206:207]
	v_pk_mul_f32 v[208:209], v[96:97], v[208:209]
	v_pk_mul_f32 v[210:211], v[86:87], v[210:211]
	v_pk_mul_f32 v[212:213], v[88:89], v[212:213]
	v_cvt_pk_bf16_f32 v214, v206, v207
	v_cvt_pk_bf16_f32 v215, v208, v209
	v_cvt_pk_bf16_f32 v216, v210, v211
	v_cvt_pk_bf16_f32 v217, v212, v213
	global_store_dwordx4 v168, v[214:217], s[8:9]
	v_pk_mul_f32 v[78:79], v[78:79], v[182:183] op_sel_hi:[1,0]
	v_pk_mul_f32 v[80:81], v[80:81], v[182:183] op_sel_hi:[1,0]
	v_pk_mul_f32 v[70:71], v[70:71], v[182:183] op_sel_hi:[1,0]
	v_pk_mul_f32 v[72:73], v[72:73], v[182:183] op_sel_hi:[1,0]
	v_pk_mul_f32 v[218:219], v[78:79], s[98:99] op_sel_hi:[1,0]
	v_pk_mul_f32 v[220:221], v[80:81], s[98:99] op_sel_hi:[1,0]
	v_pk_mul_f32 v[222:223], v[70:71], s[98:99] op_sel_hi:[1,0]
	v_pk_mul_f32 v[224:225], v[72:73], s[98:99] op_sel_hi:[1,0]
	v_pk_mul_f32 v[74:75], v[74:75], v[182:183] op_sel_hi:[1,0]
	v_pk_mul_f32 v[76:77], v[76:77], v[182:183] op_sel_hi:[1,0]
	v_pk_mul_f32 v[66:67], v[66:67], v[182:183] op_sel_hi:[1,0]
	v_pk_mul_f32 v[68:69], v[68:69], v[182:183] op_sel_hi:[1,0]
	v_exp_f32_e32 v218, v218
	v_exp_f32_e32 v219, v219
	v_exp_f32_e32 v220, v220
	v_exp_f32_e32 v221, v221
	v_exp_f32_e32 v222, v222
	v_exp_f32_e32 v223, v223
	v_exp_f32_e32 v224, v224
	v_exp_f32_e32 v225, v225
	v_pk_add_f32 v[218:219], v[218:219], s[100:101] op_sel_hi:[1,0]
	v_pk_add_f32 v[220:221], v[220:221], s[100:101] op_sel_hi:[1,0]
	v_pk_add_f32 v[222:223], v[222:223], s[100:101] op_sel_hi:[1,0]
	v_pk_add_f32 v[224:225], v[224:225], s[100:101] op_sel_hi:[1,0]
	v_rcp_f32_e32 v218, v218
	v_rcp_f32_e32 v219, v219
	v_rcp_f32_e32 v220, v220
	v_rcp_f32_e32 v221, v221
	v_rcp_f32_e32 v222, v222
	v_rcp_f32_e32 v223, v223
	v_rcp_f32_e32 v224, v224
; DI unsigned pk2(float lo, float hi) { unsigned r; asm("v_cvt_pk_bf16_f32 %0, %1, %2" : "=v"(r) : "v"(lo), "v"(hi)); return r; }
; DI float fsilu(float x) { return x * fsigmoid(x); }
;     DI void operator()(const f32x4 (&acc)[2][2][4][2], const Unit& u, int wr, int wc, int fr, int fq) const {
;     ...
;             for (int m = 0; m < 4; ++m) {
;                 const int row = rowb + ai * HALF + m * 16;
;                 float t = (sl[ai][m][0] + sl[ai][m][1]) + (sl[ai][m][2] + sl[ai][m][3]);
;                 t += __shfl_xor(t, 16); t += __shfl_xor(t, 32);
;                 const float rs = __builtin_amdgcn_rsqf(t * (1.0f / D) + EPS);
;                 float h[8];
; #pragma unroll
;                 for (int n = 0; n < 2; ++n)
; #pragma unroll
;                     for (int j = 0; j < 4; ++j) { const float gv = acc[ai][0][m][n][j] * rs, uv = acc[ai][1][m][n][j] * rs; h[n * 4 + j] = fsilu(gv) * uv; }
;                 u32x4 w; w.x = pk2(h[0], h[1]); w.y = pk2(h[2], h[3]); w.z = pk2(h[4], h[5]); w.w = pk2(h[6], h[7]);
;                 *(u32x4*)(H + (size_t)row * FF + col0) = w;
;             }
	v_rcp_f32_e32 v225, v225
	v_pk_mul_f32 v[218:219], v[78:79], v[218:219]
	v_pk_mul_f32 v[220:221], v[80:81], v[220:221]
	v_pk_mul_f32 v[222:223], v[70:71], v[222:223]
	v_pk_mul_f32 v[224:225], v[72:73], v[224:225]
	v_pk_mul_f32 v[218:219], v[74:75], v[218:219]
	v_pk_mul_f32 v[220:221], v[76:77], v[220:221]
	v_pk_mul_f32 v[222:223], v[66:67], v[222:223]
	v_pk_mul_f32 v[224:225], v[68:69], v[224:225]
	v_cvt_pk_bf16_f32 v200, v218, v219
	v_cvt_pk_bf16_f32 v201, v220, v221
	v_cvt_pk_bf16_f32 v202, v222, v223
	v_cvt_pk_bf16_f32 v203, v224, v225
	global_store_dwordx4 v169, v[200:203], s[8:9]
	v_pk_mul_f32 v[62:63], v[62:63], v[144:145] op_sel_hi:[1,0]
	v_pk_mul_f32 v[64:65], v[64:65], v[144:145] op_sel_hi:[1,0]
	v_pk_mul_f32 v[54:55], v[54:55], v[144:145] op_sel_hi:[1,0]
	v_pk_mul_f32 v[56:57], v[56:57], v[144:145] op_sel_hi:[1,0]
	v_pk_mul_f32 v[206:207], v[62:63], s[98:99] op_sel_hi:[1,0]
	v_pk_mul_f32 v[208:209], v[64:65], s[98:99] op_sel_hi:[1,0]
	v_pk_mul_f32 v[210:211], v[54:55], s[98:99] op_sel_hi:[1,0]
	v_pk_mul_f32 v[212:213], v[56:57], s[98:99] op_sel_hi:[1,0]
	v_pk_mul_f32 v[58:59], v[58:59], v[144:145] op_sel_hi:[1,0]
	v_pk_mul_f32 v[60:61], v[60:61], v[144:145] op_sel_hi:[1,0]
	v_pk_mul_f32 v[50:51], v[50:51], v[144:145] op_sel_hi:[1,0]
	v_pk_mul_f32 v[52:53], v[52:53], v[144:145] op_sel_hi:[1,0]
	v_exp_f32_e32 v206, v206
	v_exp_f32_e32 v207, v207
	v_exp_f32_e32 v208, v208
	v_exp_f32_e32 v209, v209
	v_exp_f32_e32 v210, v210
	v_exp_f32_e32 v211, v211
	v_exp_f32_e32 v212, v212
	v_exp_f32_e32 v213, v213
	v_pk_add_f32 v[206:207], v[206:207], s[100:101] op_sel_hi:[1,0]
	v_pk_add_f32 v[208:209], v[208:209], s[100:101] op_sel_hi:[1,0]
	v_pk_add_f32 v[210:211], v[210:211], s[100:101] op_sel_hi:[1,0]
	v_pk_add_f32 v[212:213], v[212:213], s[100:101] op_sel_hi:[1,0]
	v_rcp_f32_e32 v206, v206
	v_rcp_f32_e32 v207, v207
	v_rcp_f32_e32 v208, v208
	v_rcp_f32_e32 v209, v209
	v_rcp_f32_e32 v210, v210
	v_rcp_f32_e32 v211, v211
	v_rcp_f32_e32 v212, v212
	v_rcp_f32_e32 v213, v213
	v_pk_mul_f32 v[206:207], v[62:63], v[206:207]
	v_pk_mul_f32 v[208:209], v[64:65], v[208:209]
	v_pk_mul_f32 v[210:211], v[54:55], v[210:211]
	v_pk_mul_f32 v[212:213], v[56:57], v[212:213]
	v_pk_mul_f32 v[206:207], v[58:59], v[206:207]
	v_pk_mul_f32 v[208:209], v[60:61], v[208:209]
	v_pk_mul_f32 v[210:211], v[50:51], v[210:211]
	v_pk_mul_f32 v[212:213], v[52:53], v[212:213]
	v_cvt_pk_bf16_f32 v214, v206, v207
	v_cvt_pk_bf16_f32 v215, v208, v209
	v_cvt_pk_bf16_f32 v216, v210, v211
	v_cvt_pk_bf16_f32 v217, v212, v213
	global_store_dwordx4 v170, v[214:217], s[8:9]
	v_pk_mul_f32 v[46:47], v[46:47], v[146:147] op_sel_hi:[1,0]
	v_pk_mul_f32 v[48:49], v[48:49], v[146:147] op_sel_hi:[1,0]
	v_pk_mul_f32 v[38:39], v[38:39], v[146:147] op_sel_hi:[1,0]
	v_pk_mul_f32 v[40:41], v[40:41], v[146:147] op_sel_hi:[1,0]
	v_pk_mul_f32 v[218:219], v[46:47], s[98:99] op_sel_hi:[1,0]
	v_pk_mul_f32 v[220:221], v[48:49], s[98:99] op_sel_hi:[1,0]
	v_pk_mul_f32 v[222:223], v[38:39], s[98:99] op_sel_hi:[1,0]
	v_pk_mul_f32 v[224:225], v[40:41], s[98:99] op_sel_hi:[1,0]
	v_pk_mul_f32 v[42:43], v[42:43], v[146:147] op_sel_hi:[1,0]
	v_pk_mul_f32 v[44:45], v[44:45], v[146:147] op_sel_hi:[1,0]
	v_pk_mul_f32 v[34:35], v[34:35], v[146:147] op_sel_hi:[1,0]
	v_pk_mul_f32 v[36:37], v[36:37], v[146:147] op_sel_hi:[1,0]
	v_exp_f32_e32 v218, v218
	v_exp_f32_e32 v219, v219
	v_exp_f32_e32 v220, v220
	v_exp_f32_e32 v221, v221
	v_exp_f32_e32 v222, v222
	v_exp_f32_e32 v223, v223
	v_exp_f32_e32 v224, v224
	v_exp_f32_e32 v225, v225
	v_pk_add_f32 v[218:219], v[218:219], s[100:101] op_sel_hi:[1,0]
	v_pk_add_f32 v[220:221], v[220:221], s[100:101] op_sel_hi:[1,0]
	v_pk_add_f32 v[222:223], v[222:223], s[100:101] op_sel_hi:[1,0]
	v_pk_add_f32 v[224:225], v[224:225], s[100:101] op_sel_hi:[1,0]
	v_rcp_f32_e32 v218, v218
	v_rcp_f32_e32 v219, v219
	v_rcp_f32_e32 v220, v220
	v_rcp_f32_e32 v221, v221
	v_rcp_f32_e32 v222, v222
	v_rcp_f32_e32 v223, v223
	v_rcp_f32_e32 v224, v224
	v_rcp_f32_e32 v225, v225
	v_pk_mul_f32 v[218:219], v[46:47], v[218:219]
	v_pk_mul_f32 v[220:221], v[48:49], v[220:221]
	v_pk_mul_f32 v[222:223], v[38:39], v[222:223]
	v_pk_mul_f32 v[224:225], v[40:41], v[224:225]
	v_pk_mul_f32 v[218:219], v[42:43], v[218:219]
	v_pk_mul_f32 v[220:221], v[44:45], v[220:221]
	v_pk_mul_f32 v[222:223], v[34:35], v[222:223]
; DI unsigned pk2(float lo, float hi) { unsigned r; asm("v_cvt_pk_bf16_f32 %0, %1, %2" : "=v"(r) : "v"(lo), "v"(hi)); return r; }
; DI float fsilu(float x) { return x * fsigmoid(x); }
;     DI void operator()(const f32x4 (&acc)[2][2][4][2], const Unit& u, int wr, int wc, int fr, int fq) const {
;     ...
;             for (int m = 0; m < 4; ++m) {
;                 const int row = rowb + ai * HALF + m * 16;
;                 float t = (sl[ai][m][0] + sl[ai][m][1]) + (sl[ai][m][2] + sl[ai][m][3]);
;                 t += __shfl_xor(t, 16); t += __shfl_xor(t, 32);
;                 const float rs = __builtin_amdgcn_rsqf(t * (1.0f / D) + EPS);
;                 float h[8];
; #pragma unroll
;                 for (int n = 0; n < 2; ++n)
; #pragma unroll
;                     for (int j = 0; j < 4; ++j) { const float gv = acc[ai][0][m][n][j] * rs, uv = acc[ai][1][m][n][j] * rs; h[n * 4 + j] = fsilu(gv) * uv; }
;                 u32x4 w; w.x = pk2(h[0], h[1]); w.y = pk2(h[2], h[3]); w.z = pk2(h[4], h[5]); w.w = pk2(h[6], h[7]);
;                 *(u32x4*)(H + (size_t)row * FF + col0) = w;
;             }
	v_pk_mul_f32 v[224:225], v[36:37], v[224:225]
	v_cvt_pk_bf16_f32 v200, v218, v219
	v_cvt_pk_bf16_f32 v201, v220, v221
	v_cvt_pk_bf16_f32 v202, v222, v223
	v_cvt_pk_bf16_f32 v203, v224, v225
	global_store_dwordx4 v171, v[200:203], s[8:9]
	v_pk_mul_f32 v[30:31], v[30:31], v[148:149] op_sel_hi:[1,0]
	v_pk_mul_f32 v[32:33], v[32:33], v[148:149] op_sel_hi:[1,0]
	v_pk_mul_f32 v[22:23], v[22:23], v[148:149] op_sel_hi:[1,0]
	v_pk_mul_f32 v[24:25], v[24:25], v[148:149] op_sel_hi:[1,0]
	v_pk_mul_f32 v[206:207], v[30:31], s[98:99] op_sel_hi:[1,0]
	v_pk_mul_f32 v[208:209], v[32:33], s[98:99] op_sel_hi:[1,0]
	v_pk_mul_f32 v[210:211], v[22:23], s[98:99] op_sel_hi:[1,0]
	v_pk_mul_f32 v[212:213], v[24:25], s[98:99] op_sel_hi:[1,0]
	v_pk_mul_f32 v[26:27], v[26:27], v[148:149] op_sel_hi:[1,0]
	v_pk_mul_f32 v[28:29], v[28:29], v[148:149] op_sel_hi:[1,0]
	v_pk_mul_f32 v[18:19], v[18:19], v[148:149] op_sel_hi:[1,0]
	v_pk_mul_f32 v[20:21], v[20:21], v[148:149] op_sel_hi:[1,0]
	v_exp_f32_e32 v206, v206
	v_exp_f32_e32 v207, v207
	v_exp_f32_e32 v208, v208
	v_exp_f32_e32 v209, v209
	v_exp_f32_e32 v210, v210
	v_exp_f32_e32 v211, v211
	v_exp_f32_e32 v212, v212
	v_exp_f32_e32 v213, v213
	v_pk_add_f32 v[206:207], v[206:207], s[100:101] op_sel_hi:[1,0]
	v_pk_add_f32 v[208:209], v[208:209], s[100:101] op_sel_hi:[1,0]
	v_pk_add_f32 v[210:211], v[210:211], s[100:101] op_sel_hi:[1,0]
	v_pk_add_f32 v[212:213], v[212:213], s[100:101] op_sel_hi:[1,0]
	v_rcp_f32_e32 v206, v206
	v_rcp_f32_e32 v207, v207
	v_rcp_f32_e32 v208, v208
	v_rcp_f32_e32 v209, v209
	v_rcp_f32_e32 v210, v210
	v_rcp_f32_e32 v211, v211
	v_rcp_f32_e32 v212, v212
	v_rcp_f32_e32 v213, v213
	v_pk_mul_f32 v[206:207], v[30:31], v[206:207]
	v_pk_mul_f32 v[208:209], v[32:33], v[208:209]
	v_pk_mul_f32 v[210:211], v[22:23], v[210:211]
	v_pk_mul_f32 v[212:213], v[24:25], v[212:213]
	v_pk_mul_f32 v[206:207], v[26:27], v[206:207]
	v_pk_mul_f32 v[208:209], v[28:29], v[208:209]
	v_pk_mul_f32 v[210:211], v[18:19], v[210:211]
	v_pk_mul_f32 v[212:213], v[20:21], v[212:213]
	v_cvt_pk_bf16_f32 v214, v206, v207
	v_cvt_pk_bf16_f32 v215, v208, v209
	v_cvt_pk_bf16_f32 v216, v210, v211
	v_cvt_pk_bf16_f32 v217, v212, v213
	global_store_dwordx4 v172, v[214:217], s[8:9]
	v_pk_mul_f32 v[14:15], v[14:15], v[150:151] op_sel_hi:[1,0]
	v_pk_mul_f32 v[16:17], v[16:17], v[150:151] op_sel_hi:[1,0]
	v_pk_mul_f32 v[6:7], v[6:7], v[150:151] op_sel_hi:[1,0]
	v_pk_mul_f32 v[8:9], v[8:9], v[150:151] op_sel_hi:[1,0]
	v_pk_mul_f32 v[218:219], v[14:15], s[98:99] op_sel_hi:[1,0]
	v_pk_mul_f32 v[220:221], v[16:17], s[98:99] op_sel_hi:[1,0]
	v_pk_mul_f32 v[222:223], v[6:7], s[98:99] op_sel_hi:[1,0]
	v_pk_mul_f32 v[224:225], v[8:9], s[98:99] op_sel_hi:[1,0]
	v_pk_mul_f32 v[10:11], v[10:11], v[150:151] op_sel_hi:[1,0]
	v_pk_mul_f32 v[12:13], v[12:13], v[150:151] op_sel_hi:[1,0]
	v_pk_mul_f32 v[2:3], v[2:3], v[150:151] op_sel_hi:[1,0]
	v_pk_mul_f32 v[4:5], v[4:5], v[150:151] op_sel_hi:[1,0]
	v_exp_f32_e32 v218, v218
	v_exp_f32_e32 v219, v219
	v_exp_f32_e32 v220, v220
	v_exp_f32_e32 v221, v221
	v_exp_f32_e32 v222, v222
	v_exp_f32_e32 v223, v223
	v_exp_f32_e32 v224, v224
	v_exp_f32_e32 v225, v225
	v_pk_add_f32 v[218:219], v[218:219], s[100:101] op_sel_hi:[1,0]
	v_pk_add_f32 v[220:221], v[220:221], s[100:101] op_sel_hi:[1,0]
	v_pk_add_f32 v[222:223], v[222:223], s[100:101] op_sel_hi:[1,0]
	v_pk_add_f32 v[224:225], v[224:225], s[100:101] op_sel_hi:[1,0]
	v_rcp_f32_e32 v218, v218
	v_rcp_f32_e32 v219, v219
	v_rcp_f32_e32 v220, v220
	v_rcp_f32_e32 v221, v221
	v_rcp_f32_e32 v222, v222
	v_rcp_f32_e32 v223, v223
	v_rcp_f32_e32 v224, v224
	v_rcp_f32_e32 v225, v225
	v_pk_mul_f32 v[218:219], v[14:15], v[218:219]
	v_pk_mul_f32 v[220:221], v[16:17], v[220:221]
	v_pk_mul_f32 v[222:223], v[6:7], v[222:223]
	v_pk_mul_f32 v[224:225], v[8:9], v[224:225]
	v_pk_mul_f32 v[218:219], v[10:11], v[218:219]
	v_pk_mul_f32 v[220:221], v[12:13], v[220:221]
	v_pk_mul_f32 v[222:223], v[2:3], v[222:223]
	v_pk_mul_f32 v[224:225], v[4:5], v[224:225]
	v_cvt_pk_bf16_f32 v200, v218, v219
	v_cvt_pk_bf16_f32 v201, v220, v221
	v_cvt_pk_bf16_f32 v202, v222, v223
	v_cvt_pk_bf16_f32 v203, v224, v225
	global_store_dwordx4 v173, v[200:203], s[8:9]
	s_andn2_b64 vcc, exec, s[4:5]
	s_mov_b64 s[4:5], -1
	s_cbranch_vccnz .LBB0_697
	s_andn2_b64 vcc, exec, s[6:7]
	s_cbranch_vccnz .LBB0_696
	s_barrier
	s_branch .LBB0_696
